# P8 sample attention K loop: two K batches in flight (second landing zone, loop unrolled by two, counted waits +8)
# baseline (speedup 1.0000x reference)
.LBB0_1391:
	s_ashr_i32 s56, s62, 2
	s_ashr_i32 s57, s56, 31
	s_lshl_b64 s[54:55], s[56:57], 2
	s_add_u32 s54, s54, 0x4000
	s_addc_u32 s55, s55, 0
	s_lshl_b32 s20, s62, 8
	s_and_b32 s63, s20, 0x300
	s_lshl_b32 s20, s63, 1
	v_lshl_add_u64 v[2:3], v[136:137], 0, s[20:21]
	s_lshl_b64 s[58:59], s[54:55], 11
	v_lshl_add_u64 v[4:5], v[2:3], 0, s[58:59]
	s_lshl_b64 s[58:59], s[56:57], 13
	v_lshl_add_u64 v[2:3], v[2:3], 0, s[58:59]
	v_add_co_u32_e32 v6, vcc, s51, v2
	s_lshl_b64 s[56:57], s[56:57], 20
	s_nop 0
	v_addc_co_u32_e32 v7, vcc, 0, v3, vcc
	s_lshl_b32 s20, s63, 2
	v_add_co_u32_e32 v2, vcc, s60, v2
	s_or_b32 s56, s56, s20
	s_nop 0
	v_addc_co_u32_e32 v3, vcc, 0, v3, vcc
	v_lshl_add_u64 v[46:47], v[138:139], 0, s[56:57]
	global_load_dwordx2 v[34:35], v[4:5], off
	global_load_dwordx2 v[36:37], v[6:7], off offset:2048
	global_load_dwordx2 v[38:39], v[2:3], off
	global_load_dwordx2 v[40:41], v[2:3], off offset:2048
	v_lshl_add_u64 v[2:3], v[46:47], 0, s[26:27]
	v_lshl_add_u64 v[6:7], v[46:47], 0, s[28:29]
	v_lshl_add_u64 v[10:11], v[46:47], 0, s[30:31]
	v_lshl_add_u64 v[14:15], v[46:47], 0, s[34:35]
	v_lshl_add_u64 v[18:19], v[46:47], 0, s[36:37]
	v_lshl_add_u64 v[22:23], v[46:47], 0, s[38:39]
	v_lshl_add_u64 v[26:27], v[46:47], 0, s[40:41]
	v_lshl_add_u64 v[30:31], v[46:47], 0, s[42:43]
	global_load_dwordx4 v[2:5], v[2:3], off nt
	s_nop 0
	global_load_dwordx4 v[6:9], v[6:7], off nt
	s_nop 0
	global_load_dwordx4 v[10:13], v[10:11], off nt
	s_nop 0
	global_load_dwordx4 v[14:17], v[14:15], off nt
	s_nop 0
	global_load_dwordx4 v[18:21], v[18:19], off nt
	s_nop 0
	global_load_dwordx4 v[22:25], v[22:23], off nt
	s_nop 0
	global_load_dwordx4 v[26:29], v[26:27], off nt
	s_nop 0
	global_load_dwordx4 v[30:33], v[30:31], off nt
	s_mov_b64 s[100:101], 0x8000
	v_lshl_add_u64 v[224:225], v[46:47], 0, s[100:101]
	v_lshl_add_u64 v[192:193], v[224:225], 0, s[26:27]
	v_lshl_add_u64 v[196:197], v[224:225], 0, s[28:29]
	v_lshl_add_u64 v[200:201], v[224:225], 0, s[30:31]
	v_lshl_add_u64 v[204:205], v[224:225], 0, s[34:35]
	v_lshl_add_u64 v[208:209], v[224:225], 0, s[36:37]
	v_lshl_add_u64 v[212:213], v[224:225], 0, s[38:39]
	v_lshl_add_u64 v[216:217], v[224:225], 0, s[40:41]
	v_lshl_add_u64 v[220:221], v[224:225], 0, s[42:43]
	global_load_dwordx4 v[192:195], v[192:193], off nt
	s_nop 0
	global_load_dwordx4 v[196:199], v[196:197], off nt
	s_nop 0
	global_load_dwordx4 v[200:203], v[200:201], off nt
	s_nop 0
	global_load_dwordx4 v[204:207], v[204:205], off nt
	s_nop 0
	global_load_dwordx4 v[208:211], v[208:209], off nt
	s_nop 0
	global_load_dwordx4 v[212:215], v[212:213], off nt
	s_nop 0
	global_load_dwordx4 v[216:219], v[216:217], off nt
	s_nop 0
	global_load_dwordx4 v[220:223], v[220:221], off nt
	v_lshl_add_u64 v[82:83], v[140:141], 0, s[56:57]
	s_mov_b32 s20, 0
	v_lshl_add_u64 v[48:49], v[82:83], 0, s[26:27]
	v_lshl_add_u64 v[50:51], v[82:83], 0, s[28:29]
	v_lshl_add_u64 v[52:53], v[82:83], 0, s[30:31]
	v_lshl_add_u64 v[54:55], v[82:83], 0, s[34:35]
	v_lshl_add_u64 v[56:57], v[82:83], 0, s[36:37]
	v_lshl_add_u64 v[58:59], v[82:83], 0, s[38:39]
	v_lshl_add_u64 v[60:61], v[82:83], 0, s[40:41]
	v_lshl_add_u64 v[62:63], v[82:83], 0, s[42:43]
	v_mov_b32_e32 v80, v160
	s_waitcnt vmcnt(19)
	v_lshlrev_b32_e32 v64, 16, v34
	v_and_b32_e32 v65, 0xffff0000, v34
	v_lshlrev_b32_e32 v66, 16, v35
	v_and_b32_e32 v67, 0xffff0000, v35
	s_waitcnt vmcnt(18)
	v_lshlrev_b32_e32 v68, 16, v36
	v_and_b32_e32 v69, 0xffff0000, v36
	v_lshlrev_b32_e32 v70, 16, v37
	v_and_b32_e32 v71, 0xffff0000, v37
	s_waitcnt vmcnt(17)
	v_lshlrev_b32_e32 v72, 16, v38
	v_and_b32_e32 v73, 0xffff0000, v38
	v_lshlrev_b32_e32 v74, 16, v39
	v_and_b32_e32 v75, 0xffff0000, v39
	s_waitcnt vmcnt(16)
	v_lshlrev_b32_e32 v76, 16, v40
	v_and_b32_e32 v77, 0xffff0000, v40
	v_lshlrev_b32_e32 v78, 16, v41
	v_and_b32_e32 v79, 0xffff0000, v41
	s_branch .LBB0_1393

.LBB0_1393:
	s_waitcnt vmcnt(15)
	v_mov_b64_e32 v[92:93], v[4:5]
	v_mov_b64_e32 v[90:91], v[2:3]
	v_mul_f32_e32 v81, v91, v65
	v_mul_f32_e32 v110, v93, v67
	v_fmac_f32_e32 v81, v90, v64
	v_fmac_f32_e32 v110, v92, v66
	v_add_f32_e32 v81, v81, v110
	v_mul_f32_e32 v110, v91, v69
	v_mul_f32_e32 v111, v93, v71
	v_fmac_f32_e32 v110, v90, v68
	v_fmac_f32_e32 v111, v92, v70
	v_add_f32_e32 v110, v110, v111
	v_mul_f32_e32 v111, v91, v73
	v_mul_f32_e32 v91, v91, v77
	s_waitcnt vmcnt(14)
	v_mov_b64_e32 v[96:97], v[8:9]
	v_fmac_f32_e32 v111, v90, v72
	v_fmac_f32_e32 v91, v90, v76
	v_mul_f32_e32 v90, v93, v79
	v_mov_b64_e32 v[94:95], v[6:7]
	v_mul_f32_e32 v112, v93, v75
	v_fmac_f32_e32 v90, v92, v78
	v_fmac_f32_e32 v112, v92, v74
	v_add_f32_e32 v90, v91, v90
	v_mul_f32_e32 v91, v95, v65
	v_mul_f32_e32 v92, v97, v67
	v_fmac_f32_e32 v91, v94, v64
	v_fmac_f32_e32 v92, v96, v66
	v_add_f32_e32 v91, v91, v92
	v_mul_f32_e32 v92, v95, v69
	v_mul_f32_e32 v93, v97, v71
	v_fmac_f32_e32 v92, v94, v68
	v_fmac_f32_e32 v93, v96, v70
	v_add_f32_e32 v92, v92, v93
	v_mul_f32_e32 v93, v95, v73
	v_mul_f32_e32 v95, v95, v77
	s_waitcnt vmcnt(13)
	v_mov_b64_e32 v[100:101], v[12:13]
	v_fmac_f32_e32 v93, v94, v72
	v_fmac_f32_e32 v95, v94, v76
	v_mul_f32_e32 v94, v97, v79
	v_mov_b64_e32 v[98:99], v[10:11]
	v_add_f32_e32 v111, v111, v112
	v_mul_f32_e32 v112, v97, v75
	v_fmac_f32_e32 v94, v96, v78
	v_fmac_f32_e32 v112, v96, v74
	v_add_f32_e32 v94, v95, v94
	v_mul_f32_e32 v95, v99, v65
	v_mul_f32_e32 v96, v101, v67
	v_fmac_f32_e32 v95, v98, v64
	v_fmac_f32_e32 v96, v100, v66
	v_add_f32_e32 v95, v95, v96
	v_mul_f32_e32 v96, v99, v69
	v_mul_f32_e32 v97, v101, v71
	v_fmac_f32_e32 v96, v98, v68
	v_fmac_f32_e32 v97, v100, v70
	v_add_f32_e32 v96, v96, v97
	v_mul_f32_e32 v97, v99, v73
	v_mul_f32_e32 v99, v99, v77
	s_waitcnt vmcnt(12)
	v_mov_b64_e32 v[104:105], v[16:17]
	v_fmac_f32_e32 v97, v98, v72
	v_fmac_f32_e32 v99, v98, v76
	v_mul_f32_e32 v98, v101, v79
	v_mov_b64_e32 v[102:103], v[14:15]
	v_add_f32_e32 v93, v93, v112
	v_mul_f32_e32 v112, v101, v75
	v_fmac_f32_e32 v98, v100, v78
	v_fmac_f32_e32 v112, v100, v74
	v_add_f32_e32 v98, v99, v98
	v_mul_f32_e32 v99, v103, v65
	v_mul_f32_e32 v100, v105, v67
	s_cmp_gt_u32 s20, 23
	v_fmac_f32_e32 v99, v102, v64
	v_fmac_f32_e32 v100, v104, v66
	s_cselect_b64 s[56:57], -1, 0
	s_cmp_lt_u32 s20, 16
	v_add_f32_e32 v99, v99, v100
	v_mul_f32_e32 v100, v103, v69
	v_mul_f32_e32 v101, v105, v71
	s_cselect_b64 vcc, -1, 0
	s_add_i32 s64, s24, s20
	v_fmac_f32_e32 v100, v102, v68
	v_fmac_f32_e32 v101, v104, v70
	s_add_i32 s58, s64, 16
	v_add_f32_e32 v100, v100, v101
	v_mul_f32_e32 v101, v103, v73
	v_mul_f32_e32 v103, v103, v77
	s_waitcnt vmcnt(11)
	v_mov_b64_e32 v[108:109], v[20:21]
	s_ashr_i32 s59, s58, 31
	v_fmac_f32_e32 v101, v102, v72
	v_fmac_f32_e32 v103, v102, v76
	v_mul_f32_e32 v102, v105, v79
	v_mov_b64_e32 v[106:107], v[18:19]
	s_lshl_b64 s[58:59], s[58:59], 12
	v_add_f32_e32 v97, v97, v112
	v_mul_f32_e32 v112, v105, v75
	v_fmac_f32_e32 v102, v104, v78
	v_lshl_add_u64 v[2:3], v[46:47], 0, s[58:59]
	s_add_i32 s58, s64, 17
	v_fmac_f32_e32 v112, v104, v74
	v_add_f32_e32 v102, v103, v102
	v_mul_f32_e32 v103, v107, v65
	v_mul_f32_e32 v104, v109, v67
	s_ashr_i32 s59, s58, 31
	v_fmac_f32_e32 v103, v106, v64
	v_fmac_f32_e32 v104, v108, v66
	s_lshl_b64 s[58:59], s[58:59], 12
	v_add_f32_e32 v103, v103, v104
	v_mul_f32_e32 v104, v107, v69
	v_mul_f32_e32 v105, v109, v71
	v_lshl_add_u64 v[6:7], v[46:47], 0, s[58:59]
	s_add_i32 s58, s64, 18
	v_fmac_f32_e32 v104, v106, v68
	v_fmac_f32_e32 v105, v108, v70
	s_ashr_i32 s59, s58, 31
	v_add_f32_e32 v104, v104, v105
	v_mul_f32_e32 v105, v107, v73
	v_mul_f32_e32 v107, v107, v77
	s_waitcnt vmcnt(10)
	v_mov_b64_e32 v[44:45], v[24:25]
	s_lshl_b64 s[58:59], s[58:59], 12
	v_fmac_f32_e32 v105, v106, v72
	v_fmac_f32_e32 v107, v106, v76
	v_mul_f32_e32 v106, v109, v79
	v_mov_b64_e32 v[42:43], v[22:23]
	v_lshl_add_u64 v[10:11], v[46:47], 0, s[58:59]
	s_add_i32 s58, s64, 19
	v_add_f32_e32 v101, v101, v112
	v_mul_f32_e32 v112, v109, v75
	v_fmac_f32_e32 v106, v108, v78
	s_ashr_i32 s59, s58, 31
	v_fmac_f32_e32 v112, v108, v74
	v_add_f32_e32 v106, v107, v106
	v_mul_f32_e32 v107, v43, v65
	v_mul_f32_e32 v108, v45, v67
	s_lshl_b64 s[58:59], s[58:59], 12
	v_fmac_f32_e32 v107, v42, v64
	v_fmac_f32_e32 v108, v44, v66
	v_lshl_add_u64 v[14:15], v[46:47], 0, s[58:59]
	s_add_i32 s58, s64, 20
	v_add_f32_e32 v107, v107, v108
	v_mul_f32_e32 v108, v43, v69
	v_mul_f32_e32 v109, v45, v71
	s_ashr_i32 s59, s58, 31
	v_fmac_f32_e32 v108, v42, v68
	v_fmac_f32_e32 v109, v44, v70
	s_lshl_b64 s[58:59], s[58:59], 12
	v_add_f32_e32 v108, v108, v109
	v_mul_f32_e32 v109, v43, v73
	v_mul_f32_e32 v43, v43, v77
	s_waitcnt vmcnt(9)
	v_mov_b64_e32 v[40:41], v[28:29]
	v_lshl_add_u64 v[18:19], v[46:47], 0, s[58:59]
	s_add_i32 s58, s64, 21
	v_fmac_f32_e32 v109, v42, v72
	v_fmac_f32_e32 v43, v42, v76
	v_mul_f32_e32 v42, v45, v79
	v_mov_b64_e32 v[38:39], v[26:27]
	s_ashr_i32 s59, s58, 31
	v_add_f32_e32 v105, v105, v112
	v_mul_f32_e32 v112, v45, v75
	v_fmac_f32_e32 v42, v44, v78
	s_lshl_b64 s[58:59], s[58:59], 12
	v_fmac_f32_e32 v112, v44, v74
	v_add_f32_e32 v42, v43, v42
	v_mul_f32_e32 v43, v39, v65
	v_mul_f32_e32 v44, v41, v67
	v_lshl_add_u64 v[22:23], v[46:47], 0, s[58:59]
	s_add_i32 s58, s64, 22
	v_fmac_f32_e32 v43, v38, v64
	v_fmac_f32_e32 v44, v40, v66
	s_ashr_i32 s59, s58, 31
	v_add_f32_e32 v43, v43, v44
	v_mul_f32_e32 v44, v39, v69
	v_mul_f32_e32 v45, v41, v71
	s_lshl_b64 s[58:59], s[58:59], 12
	v_fmac_f32_e32 v44, v38, v68
	v_fmac_f32_e32 v45, v40, v70
	v_lshl_add_u64 v[26:27], v[46:47], 0, s[58:59]
	s_add_i32 s58, s64, 23
	v_add_f32_e32 v44, v44, v45
	v_mul_f32_e32 v45, v39, v73
	v_mul_f32_e32 v39, v39, v77
	s_waitcnt vmcnt(8) lgkmcnt(0)
	v_mov_b64_e32 v[36:37], v[32:33]
	s_ashr_i32 s59, s58, 31
	v_fmac_f32_e32 v45, v38, v72
	v_fmac_f32_e32 v39, v38, v76
	v_mul_f32_e32 v38, v41, v79
	v_mov_b64_e32 v[34:35], v[30:31]
	s_lshl_b64 s[58:59], s[58:59], 12
	v_add_f32_e32 v109, v109, v112
	v_mul_f32_e32 v112, v41, v75
	v_fmac_f32_e32 v38, v40, v78
	v_lshl_add_u64 v[30:31], v[46:47], 0, s[58:59]
	v_fmac_f32_e32 v112, v40, v74
	v_add_f32_e32 v38, v39, v38
	v_mul_f32_e32 v39, v35, v65
	v_mul_f32_e32 v40, v37, v67
	v_cndmask_b32_e32 v3, v49, v3, vcc
	v_cndmask_b32_e32 v2, v48, v2, vcc
	v_cndmask_b32_e32 v7, v51, v7, vcc
	v_cndmask_b32_e32 v6, v50, v6, vcc
	v_cndmask_b32_e32 v11, v53, v11, vcc
	v_cndmask_b32_e32 v10, v52, v10, vcc
	v_cndmask_b32_e32 v15, v55, v15, vcc
	v_cndmask_b32_e32 v14, v54, v14, vcc
	v_cndmask_b32_e32 v19, v57, v19, vcc
	v_cndmask_b32_e32 v18, v56, v18, vcc
	v_cndmask_b32_e32 v23, v59, v23, vcc
	v_cndmask_b32_e32 v22, v58, v22, vcc
	v_cndmask_b32_e32 v27, v61, v27, vcc
	v_cndmask_b32_e32 v26, v60, v26, vcc
	v_cndmask_b32_e32 v31, v63, v31, vcc
	v_cndmask_b32_e32 v30, v62, v30, vcc
	v_fmac_f32_e32 v39, v34, v64
	v_fmac_f32_e32 v40, v36, v66
	global_load_dwordx4 v[2:5], v[2:3], off nt
	v_add_f32_e32 v39, v39, v40
	global_load_dwordx4 v[6:9], v[6:7], off nt
	v_mul_f32_e32 v40, v35, v69
	global_load_dwordx4 v[10:13], v[10:11], off nt
	v_mul_f32_e32 v41, v37, v71
	global_load_dwordx4 v[14:17], v[14:15], off nt
	v_fmac_f32_e32 v40, v34, v68
	global_load_dwordx4 v[18:21], v[18:19], off nt
	v_fmac_f32_e32 v41, v36, v70
	global_load_dwordx4 v[22:25], v[22:23], off nt
	v_add_f32_e32 v45, v45, v112
	global_load_dwordx4 v[26:29], v[26:27], off nt
	v_add_f32_e32 v40, v40, v41
	global_load_dwordx4 v[30:33], v[30:31], off nt
	v_mul_f32_e32 v41, v35, v73
	v_mul_f32_e32 v112, v37, v75
	v_mul_f32_e32 v35, v35, v77
	v_mul_f32_e32 v37, v37, v79
	v_fmac_f32_e32 v41, v34, v72
	v_fmac_f32_e32 v35, v34, v76
	v_cndmask_b32_e64 v34, v81, v103, s[0:1]
	v_fmac_f32_e32 v37, v36, v78
	ds_bpermute_b32 v34, v84, v34
	v_add_f32_e32 v35, v35, v37
	v_cndmask_b32_e64 v37, v110, v104, s[0:1]
	v_fmac_f32_e32 v112, v36, v74
	v_cndmask_b32_e64 v36, v103, v81, s[0:1]
	ds_bpermute_b32 v37, v84, v37
	v_cndmask_b32_e64 v81, v111, v105, s[0:1]
	ds_bpermute_b32 v81, v84, v81
	s_waitcnt lgkmcnt(2)
	v_add_f32_e32 v34, v36, v34
	v_cndmask_b32_e64 v36, v104, v110, s[0:1]
	s_waitcnt lgkmcnt(1)
	v_add_f32_e32 v36, v36, v37
	v_cndmask_b32_e64 v37, v105, v111, s[0:1]
	v_cndmask_b32_e64 v103, v90, v106, s[0:1]
	s_waitcnt lgkmcnt(0)
	v_add_f32_e32 v37, v37, v81
	v_cndmask_b32_e64 v81, v106, v90, s[0:1]
	v_cndmask_b32_e64 v90, v107, v91, s[0:1]
	v_cndmask_b32_e64 v91, v91, v107, s[0:1]
	ds_bpermute_b32 v103, v84, v103
	ds_bpermute_b32 v91, v84, v91
	v_cndmask_b32_e64 v104, v93, v109, s[0:1]
	v_add_f32_e32 v41, v41, v112
	ds_bpermute_b32 v104, v84, v104
	s_waitcnt lgkmcnt(2)
	v_add_f32_e32 v81, v81, v103
	v_cndmask_b32_e64 v103, v92, v108, s[0:1]
	s_waitcnt lgkmcnt(1)
	v_add_f32_e32 v90, v90, v91
	v_cndmask_b32_e64 v91, v108, v92, s[0:1]
	v_cndmask_b32_e64 v92, v109, v93, s[0:1]
	v_cndmask_b32_e64 v93, v42, v94, s[0:1]
	v_cndmask_b32_e64 v42, v94, v42, s[0:1]
	ds_bpermute_b32 v42, v84, v42
	ds_bpermute_b32 v103, v84, v103
	v_cndmask_b32_e64 v94, v95, v43, s[0:1]
	ds_bpermute_b32 v94, v84, v94
	v_cndmask_b32_e64 v43, v43, v95, s[0:1]
	s_waitcnt lgkmcnt(2)
	v_add_f32_e32 v42, v93, v42
	v_cndmask_b32_e64 v93, v45, v97, s[0:1]
	v_cndmask_b32_e64 v45, v97, v45, s[0:1]
	ds_bpermute_b32 v45, v84, v45
	s_waitcnt lgkmcnt(2)
	v_add_f32_e32 v91, v91, v103
	v_cndmask_b32_e64 v103, v96, v44, s[0:1]
	ds_bpermute_b32 v103, v84, v103
	v_cndmask_b32_e64 v44, v44, v96, s[0:1]
	s_waitcnt lgkmcnt(1)
	v_add_f32_e32 v45, v93, v45
	v_cndmask_b32_e64 v93, v40, v100, s[0:1]
	v_cndmask_b32_e64 v40, v100, v40, s[0:1]
	ds_bpermute_b32 v40, v84, v40
	v_add_f32_e32 v43, v43, v94
	s_waitcnt lgkmcnt(1)
	v_add_f32_e32 v44, v44, v103
	v_cndmask_b32_e64 v94, v98, v38, s[0:1]
	v_cndmask_b32_e64 v95, v99, v39, s[0:1]
	ds_bpermute_b32 v94, v84, v94
	ds_bpermute_b32 v95, v84, v95
	s_waitcnt lgkmcnt(2)
	v_add_f32_e32 v40, v93, v40
	v_cndmask_b32_e64 v93, v43, v34, s[4:5]
	v_cndmask_b32_e64 v34, v34, v43, s[4:5]
	v_cndmask_b32_e64 v43, v36, v44, s[4:5]
	ds_bpermute_b32 v43, v85, v43
	v_cndmask_b32_e64 v38, v38, v98, s[0:1]
	v_cndmask_b32_e64 v39, v39, v99, s[0:1]
	s_waitcnt lgkmcnt(2)
	v_add_f32_e32 v38, v38, v94
	s_waitcnt lgkmcnt(1)
	v_add_f32_e32 v39, v39, v95
	v_cndmask_b32_e64 v94, v101, v41, s[0:1]
	v_cndmask_b32_e64 v95, v102, v35, s[0:1]
	v_cndmask_b32_e64 v36, v44, v36, s[4:5]
	ds_bpermute_b32 v94, v84, v94
	ds_bpermute_b32 v95, v84, v95
	s_waitcnt lgkmcnt(2)
	v_add_f32_e32 v36, v36, v43
	v_cndmask_b32_e64 v43, v38, v81, s[4:5]
	v_cndmask_b32_e64 v38, v81, v38, s[4:5]
	v_cndmask_b32_e64 v44, v90, v39, s[4:5]
	ds_bpermute_b32 v38, v85, v38
	ds_bpermute_b32 v44, v85, v44
	v_cndmask_b32_e64 v41, v41, v101, s[0:1]
	v_cndmask_b32_e64 v35, v35, v102, s[0:1]
	v_add_f32_e32 v92, v92, v104
	s_waitcnt lgkmcnt(3)
	v_add_f32_e32 v41, v41, v94
	s_waitcnt lgkmcnt(2)
	v_add_f32_e32 v35, v35, v95
	v_cndmask_b32_e64 v39, v39, v90, s[4:5]
	v_cndmask_b32_e64 v94, v37, v45, s[4:5]
	v_cndmask_b32_e64 v37, v45, v37, s[4:5]
	v_cndmask_b32_e64 v45, v91, v40, s[4:5]
	s_waitcnt lgkmcnt(1)
	v_add_f32_e32 v38, v43, v38
	s_waitcnt lgkmcnt(0)
	v_add_f32_e32 v39, v39, v44
	v_cndmask_b32_e64 v43, v41, v92, s[4:5]
	v_cndmask_b32_e64 v41, v92, v41, s[4:5]
	v_cndmask_b32_e64 v44, v42, v35, s[4:5]
	ds_bpermute_b32 v34, v85, v34
	ds_bpermute_b32 v94, v85, v94
	ds_bpermute_b32 v45, v85, v45
	ds_bpermute_b32 v41, v85, v41
	ds_bpermute_b32 v44, v85, v44
	v_cndmask_b32_e64 v40, v40, v91, s[4:5]
	v_cndmask_b32_e64 v35, v35, v42, s[4:5]
	s_waitcnt lgkmcnt(4)
	v_add_f32_e32 v34, v93, v34
	s_waitcnt lgkmcnt(3)
	v_add_f32_e32 v37, v37, v94
	s_waitcnt lgkmcnt(2)
	v_add_f32_e32 v40, v40, v45
	s_waitcnt lgkmcnt(1)
	v_add_f32_e32 v41, v43, v41
	s_waitcnt lgkmcnt(0)
	v_add_f32_e32 v35, v35, v44
	v_cndmask_b32_e64 v45, v34, v39, s[6:7]
	v_cndmask_b32_e64 v34, v39, v34, s[6:7]
	v_cndmask_b32_e64 v39, v40, v36, s[6:7]
	v_cndmask_b32_e64 v36, v36, v40, s[6:7]
	v_cndmask_b32_e64 v40, v37, v41, s[6:7]
	v_cndmask_b32_e64 v42, v38, v35, s[6:7]
	ds_bpermute_b32 v45, v86, v45
	ds_bpermute_b32 v36, v86, v36
	ds_bpermute_b32 v40, v86, v40
	ds_bpermute_b32 v42, v86, v42
	v_cndmask_b32_e64 v37, v41, v37, s[6:7]
	v_cndmask_b32_e64 v35, v35, v38, s[6:7]
	s_waitcnt lgkmcnt(3)
	v_add_f32_e32 v34, v34, v45
	s_waitcnt lgkmcnt(2)
	v_add_f32_e32 v36, v39, v36
	s_waitcnt lgkmcnt(1)
	v_add_f32_e32 v37, v37, v40
	s_waitcnt lgkmcnt(0)
	v_add_f32_e32 v35, v35, v42
	v_cndmask_b32_e64 v38, v34, v37, s[8:9]
	v_cndmask_b32_e64 v39, v36, v35, s[8:9]
	ds_bpermute_b32 v38, v87, v38
	ds_bpermute_b32 v39, v87, v39
	v_cndmask_b32_e64 v34, v37, v34, s[8:9]
	v_cndmask_b32_e64 v35, v35, v36, s[8:9]
	s_waitcnt lgkmcnt(1)
	v_add_f32_e32 v34, v34, v38
	s_waitcnt lgkmcnt(0)
	v_add_f32_e32 v35, v35, v39
	v_cndmask_b32_e64 v36, v34, v35, s[10:11]
	ds_bpermute_b32 v36, v88, v36
	v_cndmask_b32_e64 v34, v35, v34, s[10:11]
	s_waitcnt lgkmcnt(0)
	v_add_f32_e32 v34, v34, v36
	ds_bpermute_b32 v35, v89, v34
	s_and_saveexec_b64 s[58:59], s[12:13]
	s_cbranch_execz .Lk_even_end
	s_waitcnt lgkmcnt(0)
	v_add_f32_e32 v34, v34, v35
	ds_write_b32 v80, v34
.Lk_even_end:
	s_or_b64 exec, exec, s[58:59]
	s_add_i32 s20, s20, 8
	v_add_u32_e32 v80, 32, v80
	s_waitcnt vmcnt(15)
	v_mov_b64_e32 v[92:93], v[194:195]
	v_mov_b64_e32 v[90:91], v[192:193]
	v_mul_f32_e32 v81, v91, v65
	v_mul_f32_e32 v110, v93, v67
	v_fmac_f32_e32 v81, v90, v64
	v_fmac_f32_e32 v110, v92, v66
	v_add_f32_e32 v81, v81, v110
	v_mul_f32_e32 v110, v91, v69
	v_mul_f32_e32 v111, v93, v71
	v_fmac_f32_e32 v110, v90, v68
	v_fmac_f32_e32 v111, v92, v70
	v_add_f32_e32 v110, v110, v111
	v_mul_f32_e32 v111, v91, v73
	v_mul_f32_e32 v91, v91, v77
	s_waitcnt vmcnt(14)
	v_mov_b64_e32 v[96:97], v[198:199]
	v_fmac_f32_e32 v111, v90, v72
	v_fmac_f32_e32 v91, v90, v76
	v_mul_f32_e32 v90, v93, v79
	v_mov_b64_e32 v[94:95], v[196:197]
	v_mul_f32_e32 v112, v93, v75
	v_fmac_f32_e32 v90, v92, v78
	v_fmac_f32_e32 v112, v92, v74
	v_add_f32_e32 v90, v91, v90
	v_mul_f32_e32 v91, v95, v65
	v_mul_f32_e32 v92, v97, v67
	v_fmac_f32_e32 v91, v94, v64
	v_fmac_f32_e32 v92, v96, v66
	v_add_f32_e32 v91, v91, v92
	v_mul_f32_e32 v92, v95, v69
	v_mul_f32_e32 v93, v97, v71
	v_fmac_f32_e32 v92, v94, v68
	v_fmac_f32_e32 v93, v96, v70
	v_add_f32_e32 v92, v92, v93
	v_mul_f32_e32 v93, v95, v73
	v_mul_f32_e32 v95, v95, v77
	s_waitcnt vmcnt(13)
	v_mov_b64_e32 v[100:101], v[202:203]
	v_fmac_f32_e32 v93, v94, v72
	v_fmac_f32_e32 v95, v94, v76
	v_mul_f32_e32 v94, v97, v79
	v_mov_b64_e32 v[98:99], v[200:201]
	v_add_f32_e32 v111, v111, v112
	v_mul_f32_e32 v112, v97, v75
	v_fmac_f32_e32 v94, v96, v78
	v_fmac_f32_e32 v112, v96, v74
	v_add_f32_e32 v94, v95, v94
	v_mul_f32_e32 v95, v99, v65
	v_mul_f32_e32 v96, v101, v67
	v_fmac_f32_e32 v95, v98, v64
	v_fmac_f32_e32 v96, v100, v66
	v_add_f32_e32 v95, v95, v96
	v_mul_f32_e32 v96, v99, v69
	v_mul_f32_e32 v97, v101, v71
	v_fmac_f32_e32 v96, v98, v68
	v_fmac_f32_e32 v97, v100, v70
	v_add_f32_e32 v96, v96, v97
	v_mul_f32_e32 v97, v99, v73
	v_mul_f32_e32 v99, v99, v77
	s_waitcnt vmcnt(12)
	v_mov_b64_e32 v[104:105], v[206:207]
	v_fmac_f32_e32 v97, v98, v72
	v_fmac_f32_e32 v99, v98, v76
	v_mul_f32_e32 v98, v101, v79
	v_mov_b64_e32 v[102:103], v[204:205]
	v_add_f32_e32 v93, v93, v112
	v_mul_f32_e32 v112, v101, v75
	v_fmac_f32_e32 v98, v100, v78
	v_fmac_f32_e32 v112, v100, v74
	v_add_f32_e32 v98, v99, v98
	v_mul_f32_e32 v99, v103, v65
	v_mul_f32_e32 v100, v105, v67
	s_cmp_gt_u32 s20, 23
	v_fmac_f32_e32 v99, v102, v64
	v_fmac_f32_e32 v100, v104, v66
	s_cselect_b64 s[56:57], -1, 0
	s_cmp_lt_u32 s20, 16
	v_add_f32_e32 v99, v99, v100
	v_mul_f32_e32 v100, v103, v69
	v_mul_f32_e32 v101, v105, v71
	s_cselect_b64 vcc, -1, 0
	s_cmp_lt_u32 s20, 24
	s_cselect_b64 s[98:99], -1, 0
	s_add_i32 s64, s24, s20
	v_fmac_f32_e32 v100, v102, v68
	v_fmac_f32_e32 v101, v104, v70
	s_add_i32 s58, s64, 16
	v_add_f32_e32 v100, v100, v101
	v_mul_f32_e32 v101, v103, v73
	v_mul_f32_e32 v103, v103, v77
	s_waitcnt vmcnt(11)
	v_mov_b64_e32 v[108:109], v[210:211]
	s_ashr_i32 s59, s58, 31
	v_fmac_f32_e32 v101, v102, v72
	v_fmac_f32_e32 v103, v102, v76
	v_mul_f32_e32 v102, v105, v79
	v_mov_b64_e32 v[106:107], v[208:209]
	s_lshl_b64 s[58:59], s[58:59], 12
	v_add_f32_e32 v97, v97, v112
	v_mul_f32_e32 v112, v105, v75
	v_fmac_f32_e32 v102, v104, v78
	v_lshl_add_u64 v[192:193], v[46:47], 0, s[58:59]
	s_add_i32 s58, s64, 17
	v_fmac_f32_e32 v112, v104, v74
	v_add_f32_e32 v102, v103, v102
	v_mul_f32_e32 v103, v107, v65
	v_mul_f32_e32 v104, v109, v67
	s_ashr_i32 s59, s58, 31
	v_fmac_f32_e32 v103, v106, v64
	v_fmac_f32_e32 v104, v108, v66
	s_lshl_b64 s[58:59], s[58:59], 12
	v_add_f32_e32 v103, v103, v104
	v_mul_f32_e32 v104, v107, v69
	v_mul_f32_e32 v105, v109, v71
	v_lshl_add_u64 v[196:197], v[46:47], 0, s[58:59]
	s_add_i32 s58, s64, 18
	v_fmac_f32_e32 v104, v106, v68
	v_fmac_f32_e32 v105, v108, v70
	s_ashr_i32 s59, s58, 31
	v_add_f32_e32 v104, v104, v105
	v_mul_f32_e32 v105, v107, v73
	v_mul_f32_e32 v107, v107, v77
	s_waitcnt vmcnt(10)
	v_mov_b64_e32 v[44:45], v[214:215]
	s_lshl_b64 s[58:59], s[58:59], 12
	v_fmac_f32_e32 v105, v106, v72
	v_fmac_f32_e32 v107, v106, v76
	v_mul_f32_e32 v106, v109, v79
	v_mov_b64_e32 v[42:43], v[212:213]
	v_lshl_add_u64 v[200:201], v[46:47], 0, s[58:59]
	s_add_i32 s58, s64, 19
	v_add_f32_e32 v101, v101, v112
	v_mul_f32_e32 v112, v109, v75
	v_fmac_f32_e32 v106, v108, v78
	s_ashr_i32 s59, s58, 31
	v_fmac_f32_e32 v112, v108, v74
	v_add_f32_e32 v106, v107, v106
	v_mul_f32_e32 v107, v43, v65
	v_mul_f32_e32 v108, v45, v67
	s_lshl_b64 s[58:59], s[58:59], 12
	v_fmac_f32_e32 v107, v42, v64
	v_fmac_f32_e32 v108, v44, v66
	v_lshl_add_u64 v[204:205], v[46:47], 0, s[58:59]
	s_add_i32 s58, s64, 20
	v_add_f32_e32 v107, v107, v108
	v_mul_f32_e32 v108, v43, v69
	v_mul_f32_e32 v109, v45, v71
	s_ashr_i32 s59, s58, 31
	v_fmac_f32_e32 v108, v42, v68
	v_fmac_f32_e32 v109, v44, v70
	s_lshl_b64 s[58:59], s[58:59], 12
	v_add_f32_e32 v108, v108, v109
	v_mul_f32_e32 v109, v43, v73
	v_mul_f32_e32 v43, v43, v77
	s_waitcnt vmcnt(9)
	v_mov_b64_e32 v[40:41], v[218:219]
	v_lshl_add_u64 v[208:209], v[46:47], 0, s[58:59]
	s_add_i32 s58, s64, 21
	v_fmac_f32_e32 v109, v42, v72
	v_fmac_f32_e32 v43, v42, v76
	v_mul_f32_e32 v42, v45, v79
	v_mov_b64_e32 v[38:39], v[216:217]
	s_ashr_i32 s59, s58, 31
	v_add_f32_e32 v105, v105, v112
	v_mul_f32_e32 v112, v45, v75
	v_fmac_f32_e32 v42, v44, v78
	s_lshl_b64 s[58:59], s[58:59], 12
	v_fmac_f32_e32 v112, v44, v74
	v_add_f32_e32 v42, v43, v42
	v_mul_f32_e32 v43, v39, v65
	v_mul_f32_e32 v44, v41, v67
	v_lshl_add_u64 v[212:213], v[46:47], 0, s[58:59]
	s_add_i32 s58, s64, 22
	v_fmac_f32_e32 v43, v38, v64
	v_fmac_f32_e32 v44, v40, v66
	s_ashr_i32 s59, s58, 31
	v_add_f32_e32 v43, v43, v44
	v_mul_f32_e32 v44, v39, v69
	v_mul_f32_e32 v45, v41, v71
	s_lshl_b64 s[58:59], s[58:59], 12
	v_fmac_f32_e32 v44, v38, v68
	v_fmac_f32_e32 v45, v40, v70
	v_lshl_add_u64 v[216:217], v[46:47], 0, s[58:59]
	s_add_i32 s58, s64, 23
	v_add_f32_e32 v44, v44, v45
	v_mul_f32_e32 v45, v39, v73
	v_mul_f32_e32 v39, v39, v77
	s_waitcnt vmcnt(8) lgkmcnt(0)
	v_mov_b64_e32 v[36:37], v[222:223]
	s_ashr_i32 s59, s58, 31
	v_fmac_f32_e32 v45, v38, v72
	v_fmac_f32_e32 v39, v38, v76
	v_mul_f32_e32 v38, v41, v79
	v_mov_b64_e32 v[34:35], v[220:221]
	s_lshl_b64 s[58:59], s[58:59], 12
	v_add_f32_e32 v109, v109, v112
	v_mul_f32_e32 v112, v41, v75
	v_fmac_f32_e32 v38, v40, v78
	v_lshl_add_u64 v[220:221], v[46:47], 0, s[58:59]
	v_fmac_f32_e32 v112, v40, v74
	v_add_f32_e32 v38, v39, v38
	v_mul_f32_e32 v39, v35, v65
	v_mul_f32_e32 v40, v37, v67
	v_cndmask_b32_e32 v193, v49, v193, vcc
	v_cndmask_b32_e32 v192, v48, v192, vcc
	v_cndmask_b32_e32 v197, v51, v197, vcc
	v_cndmask_b32_e32 v196, v50, v196, vcc
	v_cndmask_b32_e32 v201, v53, v201, vcc
	v_cndmask_b32_e32 v200, v52, v200, vcc
	v_cndmask_b32_e32 v205, v55, v205, vcc
	v_cndmask_b32_e32 v204, v54, v204, vcc
	v_cndmask_b32_e32 v209, v57, v209, vcc
	v_cndmask_b32_e32 v208, v56, v208, vcc
	v_cndmask_b32_e32 v213, v59, v213, vcc
	v_cndmask_b32_e32 v212, v58, v212, vcc
	v_cndmask_b32_e32 v217, v61, v217, vcc
	v_cndmask_b32_e32 v216, v60, v216, vcc
	v_cndmask_b32_e32 v221, v63, v221, vcc
	v_cndmask_b32_e32 v220, v62, v220, vcc
	v_fmac_f32_e32 v39, v34, v64
	v_fmac_f32_e32 v40, v36, v66
	s_mov_b64 exec, s[98:99]
	global_load_dwordx4 v[192:195], v[192:193], off nt
	s_mov_b64 exec, -1
	v_add_f32_e32 v39, v39, v40
	s_mov_b64 exec, s[98:99]
	global_load_dwordx4 v[196:199], v[196:197], off nt
	s_mov_b64 exec, -1
	v_mul_f32_e32 v40, v35, v69
	s_mov_b64 exec, s[98:99]
	global_load_dwordx4 v[200:203], v[200:201], off nt
	s_mov_b64 exec, -1
	v_mul_f32_e32 v41, v37, v71
	s_mov_b64 exec, s[98:99]
	global_load_dwordx4 v[204:207], v[204:205], off nt
	s_mov_b64 exec, -1
	v_fmac_f32_e32 v40, v34, v68
	s_mov_b64 exec, s[98:99]
	global_load_dwordx4 v[208:211], v[208:209], off nt
	s_mov_b64 exec, -1
	v_fmac_f32_e32 v41, v36, v70
	s_mov_b64 exec, s[98:99]
	global_load_dwordx4 v[212:215], v[212:213], off nt
	s_mov_b64 exec, -1
	v_add_f32_e32 v45, v45, v112
	s_mov_b64 exec, s[98:99]
	global_load_dwordx4 v[216:219], v[216:217], off nt
	s_mov_b64 exec, -1
	v_add_f32_e32 v40, v40, v41
	s_mov_b64 exec, s[98:99]
	global_load_dwordx4 v[220:223], v[220:221], off nt
	s_mov_b64 exec, -1
	v_mul_f32_e32 v41, v35, v73
	v_mul_f32_e32 v112, v37, v75
	v_mul_f32_e32 v35, v35, v77
	v_mul_f32_e32 v37, v37, v79
	v_fmac_f32_e32 v41, v34, v72
	v_fmac_f32_e32 v35, v34, v76
	v_cndmask_b32_e64 v34, v81, v103, s[0:1]
	v_fmac_f32_e32 v37, v36, v78
	ds_bpermute_b32 v34, v84, v34
	v_add_f32_e32 v35, v35, v37
	v_cndmask_b32_e64 v37, v110, v104, s[0:1]
	v_fmac_f32_e32 v112, v36, v74
	v_cndmask_b32_e64 v36, v103, v81, s[0:1]
	ds_bpermute_b32 v37, v84, v37
	v_cndmask_b32_e64 v81, v111, v105, s[0:1]
	ds_bpermute_b32 v81, v84, v81
	s_waitcnt lgkmcnt(2)
	v_add_f32_e32 v34, v36, v34
	v_cndmask_b32_e64 v36, v104, v110, s[0:1]
	s_waitcnt lgkmcnt(1)
	v_add_f32_e32 v36, v36, v37
	v_cndmask_b32_e64 v37, v105, v111, s[0:1]
	v_cndmask_b32_e64 v103, v90, v106, s[0:1]
	s_waitcnt lgkmcnt(0)
	v_add_f32_e32 v37, v37, v81
	v_cndmask_b32_e64 v81, v106, v90, s[0:1]
	v_cndmask_b32_e64 v90, v107, v91, s[0:1]
	v_cndmask_b32_e64 v91, v91, v107, s[0:1]
	ds_bpermute_b32 v103, v84, v103
	ds_bpermute_b32 v91, v84, v91
	v_cndmask_b32_e64 v104, v93, v109, s[0:1]
	v_add_f32_e32 v41, v41, v112
	ds_bpermute_b32 v104, v84, v104
	s_waitcnt lgkmcnt(2)
	v_add_f32_e32 v81, v81, v103
	v_cndmask_b32_e64 v103, v92, v108, s[0:1]
	s_waitcnt lgkmcnt(1)
	v_add_f32_e32 v90, v90, v91
	v_cndmask_b32_e64 v91, v108, v92, s[0:1]
	v_cndmask_b32_e64 v92, v109, v93, s[0:1]
	v_cndmask_b32_e64 v93, v42, v94, s[0:1]
	v_cndmask_b32_e64 v42, v94, v42, s[0:1]
	ds_bpermute_b32 v42, v84, v42
	ds_bpermute_b32 v103, v84, v103
	v_cndmask_b32_e64 v94, v95, v43, s[0:1]
	ds_bpermute_b32 v94, v84, v94
	v_cndmask_b32_e64 v43, v43, v95, s[0:1]
	s_waitcnt lgkmcnt(2)
	v_add_f32_e32 v42, v93, v42
	v_cndmask_b32_e64 v93, v45, v97, s[0:1]
	v_cndmask_b32_e64 v45, v97, v45, s[0:1]
	ds_bpermute_b32 v45, v84, v45
	s_waitcnt lgkmcnt(2)
	v_add_f32_e32 v91, v91, v103
	v_cndmask_b32_e64 v103, v96, v44, s[0:1]
	ds_bpermute_b32 v103, v84, v103
	v_cndmask_b32_e64 v44, v44, v96, s[0:1]
	s_waitcnt lgkmcnt(1)
	v_add_f32_e32 v45, v93, v45
	v_cndmask_b32_e64 v93, v40, v100, s[0:1]
	v_cndmask_b32_e64 v40, v100, v40, s[0:1]
	ds_bpermute_b32 v40, v84, v40
	v_add_f32_e32 v43, v43, v94
	s_waitcnt lgkmcnt(1)
	v_add_f32_e32 v44, v44, v103
	v_cndmask_b32_e64 v94, v98, v38, s[0:1]
	v_cndmask_b32_e64 v95, v99, v39, s[0:1]
	ds_bpermute_b32 v94, v84, v94
	ds_bpermute_b32 v95, v84, v95
	s_waitcnt lgkmcnt(2)
	v_add_f32_e32 v40, v93, v40
	v_cndmask_b32_e64 v93, v43, v34, s[4:5]
	v_cndmask_b32_e64 v34, v34, v43, s[4:5]
	v_cndmask_b32_e64 v43, v36, v44, s[4:5]
	ds_bpermute_b32 v43, v85, v43
	v_cndmask_b32_e64 v38, v38, v98, s[0:1]
	v_cndmask_b32_e64 v39, v39, v99, s[0:1]
	s_waitcnt lgkmcnt(2)
	v_add_f32_e32 v38, v38, v94
	s_waitcnt lgkmcnt(1)
	v_add_f32_e32 v39, v39, v95
	v_cndmask_b32_e64 v94, v101, v41, s[0:1]
	v_cndmask_b32_e64 v95, v102, v35, s[0:1]
	v_cndmask_b32_e64 v36, v44, v36, s[4:5]
	ds_bpermute_b32 v94, v84, v94
	ds_bpermute_b32 v95, v84, v95
	s_waitcnt lgkmcnt(2)
	v_add_f32_e32 v36, v36, v43
	v_cndmask_b32_e64 v43, v38, v81, s[4:5]
	v_cndmask_b32_e64 v38, v81, v38, s[4:5]
	v_cndmask_b32_e64 v44, v90, v39, s[4:5]
	ds_bpermute_b32 v38, v85, v38
	ds_bpermute_b32 v44, v85, v44
	v_cndmask_b32_e64 v41, v41, v101, s[0:1]
	v_cndmask_b32_e64 v35, v35, v102, s[0:1]
	v_add_f32_e32 v92, v92, v104
	s_waitcnt lgkmcnt(3)
	v_add_f32_e32 v41, v41, v94
	s_waitcnt lgkmcnt(2)
	v_add_f32_e32 v35, v35, v95
	v_cndmask_b32_e64 v39, v39, v90, s[4:5]
	v_cndmask_b32_e64 v94, v37, v45, s[4:5]
	v_cndmask_b32_e64 v37, v45, v37, s[4:5]
	v_cndmask_b32_e64 v45, v91, v40, s[4:5]
	s_waitcnt lgkmcnt(1)
	v_add_f32_e32 v38, v43, v38
	s_waitcnt lgkmcnt(0)
	v_add_f32_e32 v39, v39, v44
	v_cndmask_b32_e64 v43, v41, v92, s[4:5]
	v_cndmask_b32_e64 v41, v92, v41, s[4:5]
	v_cndmask_b32_e64 v44, v42, v35, s[4:5]
	ds_bpermute_b32 v34, v85, v34
	ds_bpermute_b32 v94, v85, v94
	ds_bpermute_b32 v45, v85, v45
	ds_bpermute_b32 v41, v85, v41
	ds_bpermute_b32 v44, v85, v44
	v_cndmask_b32_e64 v40, v40, v91, s[4:5]
	v_cndmask_b32_e64 v35, v35, v42, s[4:5]
	s_waitcnt lgkmcnt(4)
	v_add_f32_e32 v34, v93, v34
	s_waitcnt lgkmcnt(3)
	v_add_f32_e32 v37, v37, v94
	s_waitcnt lgkmcnt(2)
	v_add_f32_e32 v40, v40, v45
	s_waitcnt lgkmcnt(1)
	v_add_f32_e32 v41, v43, v41
	s_waitcnt lgkmcnt(0)
	v_add_f32_e32 v35, v35, v44
	v_cndmask_b32_e64 v45, v34, v39, s[6:7]
	v_cndmask_b32_e64 v34, v39, v34, s[6:7]
	v_cndmask_b32_e64 v39, v40, v36, s[6:7]
	v_cndmask_b32_e64 v36, v36, v40, s[6:7]
	v_cndmask_b32_e64 v40, v37, v41, s[6:7]
	v_cndmask_b32_e64 v42, v38, v35, s[6:7]
	ds_bpermute_b32 v45, v86, v45
	ds_bpermute_b32 v36, v86, v36
	ds_bpermute_b32 v40, v86, v40
	ds_bpermute_b32 v42, v86, v42
	v_cndmask_b32_e64 v37, v41, v37, s[6:7]
	v_cndmask_b32_e64 v35, v35, v38, s[6:7]
	s_waitcnt lgkmcnt(3)
	v_add_f32_e32 v34, v34, v45
	s_waitcnt lgkmcnt(2)
	v_add_f32_e32 v36, v39, v36
	s_waitcnt lgkmcnt(1)
	v_add_f32_e32 v37, v37, v40
	s_waitcnt lgkmcnt(0)
	v_add_f32_e32 v35, v35, v42
	v_cndmask_b32_e64 v38, v34, v37, s[8:9]
	v_cndmask_b32_e64 v39, v36, v35, s[8:9]
	ds_bpermute_b32 v38, v87, v38
	ds_bpermute_b32 v39, v87, v39
	v_cndmask_b32_e64 v34, v37, v34, s[8:9]
	v_cndmask_b32_e64 v35, v35, v36, s[8:9]
	s_waitcnt lgkmcnt(1)
	v_add_f32_e32 v34, v34, v38
	s_waitcnt lgkmcnt(0)
	v_add_f32_e32 v35, v35, v39
	v_cndmask_b32_e64 v36, v34, v35, s[10:11]
	ds_bpermute_b32 v36, v88, v36
	v_cndmask_b32_e64 v34, v35, v34, s[10:11]
	s_waitcnt lgkmcnt(0)
	v_add_f32_e32 v34, v34, v36
	ds_bpermute_b32 v35, v89, v34
	s_and_saveexec_b64 s[58:59], s[12:13]
	s_cbranch_execz .LBB0_1392
	s_waitcnt lgkmcnt(0)
	v_add_f32_e32 v34, v34, v35
	ds_write_b32 v80, v34
	s_branch .LBB0_1392
